# hg_prep cumulative sum unrolled: all sixteen LDS read pairs issued first, same add order, write-backs at the end
# speedup vs baseline: 1.0040x; 1.0025x over previous
; #define LAS __attribute__((address_space(3)))
; #define LDSBAR() do { asm volatile("s_waitcnt lgkmcnt(0)" ::: "memory"); __builtin_amdgcn_s_barrier(); asm volatile("" ::: "memory"); } while (0)
; __device__ __forceinline__ void hg_prep(const Frame& F, unsigned char* ws, unsigned char* sfr) {
;     ...
;         *(LAS f32x4*)(LB + c * 132 + 8 * kg) = lf0; *(LAS f32x4*)(LB + c * 132 + 8 * kg + 4) = lf1;
;         { const unsigned vv[4] = {v8.x, v8.y, v8.z, v8.w};
; #pragma unroll
;           for (int j = 0; j < 4; ++j) { VT[(8 * kg + 2 * j) * 40 + c] = (bf16)(vv[j] & 0xffffu); VT[(8 * kg + 2 * j + 1) * 40 + c] = (bf16)(vv[j] >> 16); } }
;         LDSBAR();
;         if (tid < 128) { float run = 0.f;
; #pragma unroll 8
;             for (int cc = 0; cc < 32; ++cc) { run += LB[cc * 132 + tid]; LB[cc * 132 + tid] = run; } }
.Lhgpf_none:
.LBB0_441:
	ds_write_b128 v23, v[18:21]
	ds_write_b128 v23, v[2:5] offset:16
	ds_write_b16 v45, v10 offset:44544
	ds_write_b16_d16_hi v45, v10 offset:44624
	ds_write_b16 v45, v11 offset:44704
	ds_write_b16_d16_hi v45, v11 offset:44784
	ds_write_b16 v45, v12 offset:44864
	ds_write_b16_d16_hi v45, v12 offset:44944
	ds_write_b16 v45, v13 offset:45024
	ds_write_b16_d16_hi v45, v13 offset:45104
	s_waitcnt lgkmcnt(0)
	s_barrier
	s_and_saveexec_b64 s[58:59], s[6:7]
	s_cbranch_execz .LBB0_444
	v_mov_b32_e32 v10, 0
	v_mov_b32_e32 v132, v38
	v_add_u32_e32 v133, 0x400, v132
	v_add_u32_e32 v134, 0x800, v132
	v_add_u32_e32 v135, 0xc00, v132
	v_add_u32_e32 v136, 0x1080, v38
	v_add_u32_e32 v137, 0x400, v136
	v_add_u32_e32 v138, 0x800, v136
	v_add_u32_e32 v139, 0xc00, v136
	v_add_u32_e32 v140, 0x2100, v38
	v_add_u32_e32 v141, 0x400, v140
	v_add_u32_e32 v142, 0x800, v140
	v_add_u32_e32 v143, 0xc00, v140
	v_add_u32_e32 v144, 0x3180, v38
	v_add_u32_e32 v145, 0x400, v144
	v_add_u32_e32 v146, 0x800, v144
	v_add_u32_e32 v147, 0xc00, v144
	ds_read2_b32 v[100:101], v132 offset1:132
	ds_read2_b32 v[102:103], v133 offset0:8 offset1:140
	ds_read2_b32 v[104:105], v134 offset0:16 offset1:148
	ds_read2_b32 v[106:107], v135 offset0:24 offset1:156
	ds_read2_b32 v[108:109], v136 offset1:132
	ds_read2_b32 v[110:111], v137 offset0:8 offset1:140
	ds_read2_b32 v[112:113], v138 offset0:16 offset1:148
	ds_read2_b32 v[114:115], v139 offset0:24 offset1:156
	ds_read2_b32 v[116:117], v140 offset1:132
	ds_read2_b32 v[118:119], v141 offset0:8 offset1:140
	ds_read2_b32 v[120:121], v142 offset0:16 offset1:148
	ds_read2_b32 v[122:123], v143 offset0:24 offset1:156
	ds_read2_b32 v[124:125], v144 offset1:132
	ds_read2_b32 v[126:127], v145 offset0:8 offset1:140
	ds_read2_b32 v[128:129], v146 offset0:16 offset1:148
	s_waitcnt lgkmcnt(14)
	v_add_f32_e32 v100, v10, v100
	v_add_f32_e32 v101, v100, v101
	ds_read2_b32 v[130:131], v147 offset0:24 offset1:156
	s_waitcnt lgkmcnt(14)
	v_add_f32_e32 v102, v101, v102
	v_add_f32_e32 v103, v102, v103
	s_waitcnt lgkmcnt(13)
	v_add_f32_e32 v104, v103, v104
	v_add_f32_e32 v105, v104, v105
	s_waitcnt lgkmcnt(12)
	v_add_f32_e32 v106, v105, v106
	v_add_f32_e32 v107, v106, v107
	s_waitcnt lgkmcnt(11)
	v_add_f32_e32 v108, v107, v108
	v_add_f32_e32 v109, v108, v109
	s_waitcnt lgkmcnt(10)
	v_add_f32_e32 v110, v109, v110
	v_add_f32_e32 v111, v110, v111
	s_waitcnt lgkmcnt(9)
	v_add_f32_e32 v112, v111, v112
	v_add_f32_e32 v113, v112, v113
	s_waitcnt lgkmcnt(8)
	v_add_f32_e32 v114, v113, v114
	v_add_f32_e32 v115, v114, v115
	s_waitcnt lgkmcnt(7)
	v_add_f32_e32 v116, v115, v116
	v_add_f32_e32 v117, v116, v117
	s_waitcnt lgkmcnt(6)
	v_add_f32_e32 v118, v117, v118
	v_add_f32_e32 v119, v118, v119
	s_waitcnt lgkmcnt(5)
	v_add_f32_e32 v120, v119, v120
	v_add_f32_e32 v121, v120, v121
	s_waitcnt lgkmcnt(4)
	v_add_f32_e32 v122, v121, v122
	v_add_f32_e32 v123, v122, v123
	s_waitcnt lgkmcnt(3)
	v_add_f32_e32 v124, v123, v124
	v_add_f32_e32 v125, v124, v125
	s_waitcnt lgkmcnt(2)
	v_add_f32_e32 v126, v125, v126
	v_add_f32_e32 v127, v126, v127
	s_waitcnt lgkmcnt(1)
	v_add_f32_e32 v128, v127, v128
	v_add_f32_e32 v129, v128, v129
	s_waitcnt lgkmcnt(0)
	v_add_f32_e32 v130, v129, v130
	v_add_f32_e32 v131, v130, v131
	ds_write2_b32 v132, v100, v101 offset1:132
	ds_write2_b32 v133, v102, v103 offset0:8 offset1:140
	ds_write2_b32 v134, v104, v105 offset0:16 offset1:148
	ds_write2_b32 v135, v106, v107 offset0:24 offset1:156
	ds_write2_b32 v136, v108, v109 offset1:132
	ds_write2_b32 v137, v110, v111 offset0:8 offset1:140
	ds_write2_b32 v138, v112, v113 offset0:16 offset1:148
	ds_write2_b32 v139, v114, v115 offset0:24 offset1:156
	ds_write2_b32 v140, v116, v117 offset1:132
	ds_write2_b32 v141, v118, v119 offset0:8 offset1:140
	ds_write2_b32 v142, v120, v121 offset0:16 offset1:148
	ds_write2_b32 v143, v122, v123 offset0:24 offset1:156
	ds_write2_b32 v144, v124, v125 offset1:132
	ds_write2_b32 v145, v126, v127 offset0:8 offset1:140
	ds_write2_b32 v146, v128, v129 offset0:16 offset1:148
	ds_write2_b32 v147, v130, v131 offset0:24 offset1:156
	s_movk_i32 s42, 0x4200
